# v20 + P0 rmsnorm loop: gain loads hoisted out of the loop, wave sums via DPP/permlane swaps
# speedup vs baseline: 1.0057x; 1.0006x over previous
; DI unsigned pk2(float lo, float hi) { return pg8::cvt_pk_bf16(lo, hi); }
; DI void norm_row2_bf16(const float* xa, const float* xb, const float* g, bf16* oa, bf16* ob, int lane) {
;     f32x4 va[4], vb[4]; float sa = 0.f, sb = 0.f;
; #pragma unroll
;     for (int j = 0; j < 4; ++j) { va[j] = *(const f32x4*)(xa + 256 * j + 4 * lane); vb[j] = *(const f32x4*)(xb + 256 * j + 4 * lane); }
; #pragma unroll
;     for (int j = 0; j < 4; ++j) { sa += (va[j][0] * va[j][0] + va[j][1] * va[j][1]) + (va[j][2] * va[j][2] + va[j][3] * va[j][3]); sb += (vb[j][0] * vb[j][0] + vb[j][1] * vb[j][1]) + (vb[j][2] * vb[j][2] + vb[j][3] * vb[j][3]); }
;     const float ra = __builtin_amdgcn_rsqf(wave_sum(sa) * (1.f / 1024.f) + EPS), rb = __builtin_amdgcn_rsqf(wave_sum(sb) * (1.f / 1024.f) + EPS);
; #pragma unroll
;     for (int j = 0; j < 4; ++j) { const f32x4 gg = *(const f32x4*)(g + 256 * j + 4 * lane);
;         u32x2 o; o.x = pk2(va[j][0] * ra * gg[0], va[j][1] * ra * gg[1]); o.y = pk2(va[j][2] * ra * gg[2], va[j][3] * ra * gg[3]); *(u32x2*)(oa + 256 * j + 4 * lane) = o;
;         u32x2 p; p.x = pk2(vb[j][0] * rb * gg[0], vb[j][1] * rb * gg[1]); p.y = pk2(vb[j][2] * rb * gg[2], vb[j][3] * rb * gg[3]); *(u32x2*)(ob + 256 * j + 4 * lane) = p; }
; }
; __global__ void __launch_bounds__(512, 2) fwd_megakernel(Params P) {
;     ...
;         { int m = gw;
;           for (; m + NGW < T; m += 2 * NGW) norm_row2_bf16(P.x + (size_t)m * 1024, P.x + (size_t)(m + NGW) * 1024, P.norm_mix, HB + (size_t)m * 1024, HB + (size_t)(m + NGW) * 1024, lane);
;           for (; m < T; m += NGW) norm_row_bf16(P.x + (size_t)m * 1024, P.norm_mix, HB + (size_t)m * 1024, lane); }
.LBB0_402:
	s_lshl_b32 s12, s34, 4
	s_add_i32 s14, s4, s28
	s_cmpk_gt_i32 s14, 0x7fff
	v_lshlrev_b32_e32 v12, 4, v11
	s_mov_b32 s2, s4
	s_cbranch_scc1 .LBB0_406
	v_mbcnt_lo_u32_b32 v0, -1, 0
	v_mbcnt_hi_u32_b32 v0, -1, v0
	v_and_b32_e32 v1, 64, v0
	v_add_u32_e32 v1, 64, v1
	v_xor_b32_e32 v2, 1, v0
	v_cmp_lt_i32_e32 vcc, v2, v1
	v_mov_b32_e32 v13, 0
	v_mov_b32_e32 v11, v13
	v_cndmask_b32_e32 v2, v0, v2, vcc
	v_lshlrev_b32_e32 v24, 2, v2
	v_xor_b32_e32 v2, 2, v0
	v_cmp_lt_i32_e32 vcc, v2, v1
	s_mov_b64 s[0:1], 0x2000000
	s_ashr_i32 s5, s4, 31
	v_cndmask_b32_e32 v2, v0, v2, vcc
	v_lshlrev_b32_e32 v25, 2, v2
	v_xor_b32_e32 v2, 4, v0
	v_cmp_lt_i32_e32 vcc, v2, v1
	s_lshl_b64 s[2:3], s[4:5], 11
	v_lshl_add_u64 v[14:15], s[36:37], 0, v[12:13]
	v_cndmask_b32_e32 v2, v0, v2, vcc
	v_lshlrev_b32_e32 v26, 2, v2
	v_xor_b32_e32 v2, 8, v0
	v_cmp_lt_i32_e32 vcc, v2, v1
	v_lshl_add_u64 v[16:17], s[42:43], 0, v[12:13]
	s_nop 0
	v_cndmask_b32_e32 v2, v0, v2, vcc
	v_lshlrev_b32_e32 v27, 2, v2
	v_xor_b32_e32 v2, 16, v0
	v_cmp_lt_i32_e32 vcc, v2, v1
	s_nop 1
	v_cndmask_b32_e32 v2, v0, v2, vcc
	v_lshlrev_b32_e32 v28, 2, v2
	v_xor_b32_e32 v2, 32, v0
	v_cmp_lt_i32_e32 vcc, v2, v1
	s_nop 1
	v_cndmask_b32_e32 v0, v0, v2, vcc
	v_lshlrev_b32_e32 v29, 2, v0
	v_lshl_add_u64 v[0:1], s[68:69], 0, v[10:11]
	v_lshl_add_u64 v[18:19], v[0:1], 0, s[0:1]
	s_add_i32 s0, s33, s34
	s_lshl_b32 s0, s0, 3
	s_add_u32 s1, s8, s2
	s_addc_u32 s3, s9, s3
	s_add_u32 s2, s26, s1
	s_addc_u32 s3, s27, s3
	v_lshl_add_u64 v[0:1], s[2:3], 0, v[10:11]
	s_mov_b64 s[2:3], 0x2000400
	s_ashr_i32 s13, s12, 31
	v_lshl_add_u64 v[20:21], v[0:1], 0, s[2:3]
	s_lshl_b64 s[2:3], s[12:13], 11
	s_lshl_b64 s[6:7], s[4:5], 12
	s_add_u32 s6, s36, s6
	s_addc_u32 s7, s37, s7
	v_lshl_add_u64 v[0:1], s[6:7], 0, v[12:13]
	s_mov_b64 s[6:7], 0xc00
	v_lshl_add_u64 v[22:23], v[0:1], 0, s[6:7]
	s_lshl_b64 s[6:7], s[12:13], 12
	v_mov_b32_e32 v11, 0x358637bd
	s_mov_b32 s1, s4
	global_load_dwordx4 v[228:231], v[16:17], off
	global_load_dwordx4 v[232:235], v[16:17], off offset:1024
	global_load_dwordx4 v[236:239], v[16:17], off offset:2048
	global_load_dwordx4 v[244:247], v[16:17], off offset:3072
; DI unsigned pk2(float lo, float hi) { return pg8::cvt_pk_bf16(lo, hi); }
; DI void norm_row2_bf16(const float* xa, const float* xb, const float* g, bf16* oa, bf16* ob, int lane) {
;     f32x4 va[4], vb[4]; float sa = 0.f, sb = 0.f;
; #pragma unroll
;     for (int j = 0; j < 4; ++j) { va[j] = *(const f32x4*)(xa + 256 * j + 4 * lane); vb[j] = *(const f32x4*)(xb + 256 * j + 4 * lane); }
; #pragma unroll
;     for (int j = 0; j < 4; ++j) { sa += (va[j][0] * va[j][0] + va[j][1] * va[j][1]) + (va[j][2] * va[j][2] + va[j][3] * va[j][3]); sb += (vb[j][0] * vb[j][0] + vb[j][1] * vb[j][1]) + (vb[j][2] * vb[j][2] + vb[j][3] * vb[j][3]); }
;     const float ra = __builtin_amdgcn_rsqf(wave_sum(sa) * (1.f / 1024.f) + EPS), rb = __builtin_amdgcn_rsqf(wave_sum(sb) * (1.f / 1024.f) + EPS);
; #pragma unroll
;     for (int j = 0; j < 4; ++j) { const f32x4 gg = *(const f32x4*)(g + 256 * j + 4 * lane);
;         u32x2 o; o.x = pk2(va[j][0] * ra * gg[0], va[j][1] * ra * gg[1]); o.y = pk2(va[j][2] * ra * gg[2], va[j][3] * ra * gg[3]); *(u32x2*)(oa + 256 * j + 4 * lane) = o;
;         u32x2 p; p.x = pk2(vb[j][0] * rb * gg[0], vb[j][1] * rb * gg[1]); p.y = pk2(vb[j][2] * rb * gg[2], vb[j][3] * rb * gg[3]); *(u32x2*)(ob + 256 * j + 4 * lane) = p; }
; }
.LBB0_404:
	global_load_dwordx4 v[30:33], v[22:23], off offset:-3072
	global_load_dwordx4 v[34:37], v[22:23], off offset:-2048
	global_load_dwordx4 v[4:7], v[22:23], off offset:-1024
	global_load_dwordx4 v[0:3], v[22:23], off
	s_ashr_i32 s15, s14, 31
	s_lshl_b64 s[10:11], s[14:15], 12
	v_lshl_add_u64 v[58:59], v[14:15], 0, s[10:11]
	global_load_dwordx4 v[42:45], v[58:59], off
	global_load_dwordx4 v[46:49], v[58:59], off offset:1024
	global_load_dwordx4 v[50:53], v[58:59], off offset:2048
	global_load_dwordx4 v[54:57], v[58:59], off offset:3072
	s_lshl_b64 s[14:15], s[14:15], 11
	v_lshl_add_u64 v[60:61], v[18:19], 0, s[14:15]
	s_add_i32 s1, s1, s12
	s_add_i32 s29, s29, s12
	s_add_i32 s14, s1, s28
	s_add_i32 s5, s0, s29
	v_lshl_add_u64 v[22:23], v[22:23], 0, s[6:7]
	s_cmpk_gt_i32 s5, 0x7fff
	s_waitcnt vmcnt(7)
	v_mul_f32_e32 v13, v31, v31
	v_mul_f32_e32 v58, v33, v33
	s_waitcnt vmcnt(6)
	v_mul_f32_e32 v59, v35, v35
	v_mul_f32_e32 v62, v37, v37
	s_waitcnt vmcnt(5)
	v_mul_f32_e32 v63, v5, v5
	v_mul_f32_e32 v64, v7, v7
	s_waitcnt vmcnt(4)
	v_mul_f32_e32 v65, v1, v1
	v_mul_f32_e32 v66, v3, v3
	v_fmac_f32_e32 v13, v30, v30
	v_fmac_f32_e32 v58, v32, v32
	v_fmac_f32_e32 v59, v34, v34
	v_fmac_f32_e32 v62, v36, v36
	v_fmac_f32_e32 v63, v4, v4
	v_fmac_f32_e32 v64, v6, v6
	v_fmac_f32_e32 v65, v0, v0
	v_fmac_f32_e32 v66, v2, v2
	v_add_f32_e32 v13, v13, v58
	v_add_f32_e32 v58, v59, v62
	v_add_f32_e32 v59, v63, v64
	v_add_f32_e32 v62, v65, v66
	s_waitcnt vmcnt(3)
	v_mul_f32_e32 v63, v43, v43
	v_mul_f32_e32 v64, v45, v45
	v_add_f32_e32 v13, v13, v58
	s_waitcnt vmcnt(2)
	v_mul_f32_e32 v58, v47, v47
	v_mul_f32_e32 v65, v49, v49
	s_waitcnt vmcnt(1)
	v_mul_f32_e32 v66, v51, v51
	v_mul_f32_e32 v67, v53, v53
	v_fmac_f32_e32 v63, v42, v42
	v_fmac_f32_e32 v64, v44, v44
	v_fmac_f32_e32 v58, v46, v46
	v_fmac_f32_e32 v65, v48, v48
	v_add_f32_e32 v13, v13, v59
	s_waitcnt vmcnt(0)
	v_mul_f32_e32 v68, v55, v55
	v_mul_f32_e32 v69, v57, v57
	v_fmac_f32_e32 v66, v50, v50
	v_fmac_f32_e32 v67, v52, v52
	v_add_f32_e32 v59, v63, v64
	v_add_f32_e32 v58, v58, v65
	v_add_f32_e32 v13, v13, v62
	v_fmac_f32_e32 v68, v54, v54
	v_fmac_f32_e32 v69, v56, v56
	v_add_f32_e32 v63, v66, v67
	v_add_f32_e32 v58, v59, v58
	v_add_f32_e32 v62, v68, v69
	v_add_f32_e32 v58, v58, v63
	v_add_f32_e32 v58, v58, v62
	s_nop 1
	v_add_f32_dpp v13, v13, v13 quad_perm:[1,0,3,2] row_mask:0xf bank_mask:0xf
	s_nop 1
	v_add_f32_dpp v58, v58, v58 quad_perm:[1,0,3,2] row_mask:0xf bank_mask:0xf
	s_nop 1
	v_add_f32_dpp v13, v13, v13 quad_perm:[2,3,0,1] row_mask:0xf bank_mask:0xf
	s_nop 1
	v_add_f32_dpp v58, v58, v58 quad_perm:[2,3,0,1] row_mask:0xf bank_mask:0xf
	s_nop 1
	v_add_f32_dpp v13, v13, v13 row_half_mirror row_mask:0xf bank_mask:0xf
	s_nop 1
	v_add_f32_dpp v58, v58, v58 row_half_mirror row_mask:0xf bank_mask:0xf
	s_nop 1
	v_add_f32_dpp v13, v13, v13 row_mirror row_mask:0xf bank_mask:0xf
	v_mov_b32_e32 v59, v13
	s_nop 1
	v_add_f32_dpp v58, v58, v58 row_mirror row_mask:0xf bank_mask:0xf
	v_mov_b32_e32 v62, v58
	s_nop 1
	v_permlane16_swap_b32_e32 v59, v13
	v_add_f32_e32 v13, v13, v59
	v_mov_b32_e32 v59, v13
	s_nop 1
	v_permlane16_swap_b32_e32 v62, v58
	v_add_f32_e32 v58, v58, v62
	v_mov_b32_e32 v62, v58
	s_nop 1
	v_permlane32_swap_b32_e32 v59, v13
	v_add_f32_e32 v13, v13, v59
	v_fmamk_f32 v13, v13, 0x3a800000, v11
	v_rsq_f32_e32 v13, v13
	s_nop 1
	v_permlane32_swap_b32_e32 v62, v58
	v_add_f32_e32 v58, v58, v62
	v_fmamk_f32 v58, v58, 0x3a800000, v11
	v_rsq_f32_e32 v58, v58
	v_mov_b32_e32 v38, v228
	v_mov_b32_e32 v39, v229
	v_mov_b32_e32 v40, v230
	v_mov_b32_e32 v41, v231
	v_mul_f32_e32 v30, v30, v13
	v_mul_f32_e32 v31, v31, v13
	v_mul_f32_e32 v32, v32, v13
	v_mul_f32_e32 v33, v33, v13
	v_mul_f32_e32 v30, v30, v38
	v_mul_f32_e32 v31, v31, v39
	v_mul_f32_e32 v32, v32, v40
	v_mul_f32_e32 v33, v33, v41
	v_cvt_pk_bf16_f32 v30, v30, v31
	v_cvt_pk_bf16_f32 v31, v32, v33
	global_store_dwordx2 v[20:21], v[30:31], off offset:-1024
	v_mul_f32_e32 v30, v42, v58
	v_mul_f32_e32 v31, v43, v58
	v_mul_f32_e32 v32, v44, v58
	v_mul_f32_e32 v33, v45, v58
	v_mul_f32_e32 v30, v38, v30
	v_mul_f32_e32 v31, v39, v31
	v_mul_f32_e32 v32, v40, v32
	v_mul_f32_e32 v33, v41, v33
	v_cvt_pk_bf16_f32 v30, v30, v31
	v_cvt_pk_bf16_f32 v31, v32, v33
	global_store_dwordx2 v[60:61], v[30:31], off
	v_mul_f32_e32 v34, v34, v13
	v_mul_f32_e32 v35, v35, v13
	v_mul_f32_e32 v36, v36, v13
	v_mul_f32_e32 v37, v37, v13
	v_mul_f32_e32 v38, v46, v58
	v_mul_f32_e32 v39, v47, v58
	v_mul_f32_e32 v41, v49, v58
	v_mul_f32_e32 v40, v48, v58
	v_mul_f32_e32 v4, v4, v13
	v_mul_f32_e32 v5, v5, v13
	v_mul_f32_e32 v6, v6, v13
	v_mul_f32_e32 v7, v7, v13
	v_mul_f32_e32 v0, v0, v13
	v_mul_f32_e32 v1, v1, v13
	v_mul_f32_e32 v2, v2, v13
	v_mul_f32_e32 v3, v3, v13
	v_mul_f32_e32 v13, v54, v58
	v_mov_b32_e32 v30, v232
	v_mov_b32_e32 v31, v233
	v_mov_b32_e32 v32, v234
	v_mov_b32_e32 v33, v235
	v_mul_f32_e32 v34, v34, v30
	v_mul_f32_e32 v35, v35, v31
	v_mul_f32_e32 v36, v36, v32
	v_mul_f32_e32 v37, v37, v33
	v_mul_f32_e32 v38, v38, v30
	v_mul_f32_e32 v39, v39, v31
	v_mul_f32_e32 v33, v41, v33
	v_cvt_pk_bf16_f32 v30, v34, v35
	v_cvt_pk_bf16_f32 v31, v36, v37
	v_mul_f32_e32 v40, v40, v32
	v_cvt_pk_bf16_f32 v32, v38, v39
	v_cvt_pk_bf16_f32 v33, v40, v33
	global_store_dwordx2 v[20:21], v[30:31], off offset:-512
	global_store_dwordx2 v[60:61], v[32:33], off offset:512
	v_mul_f32_e32 v34, v50, v58
	v_mul_f32_e32 v35, v51, v58
	v_mul_f32_e32 v36, v52, v58
	v_mul_f32_e32 v37, v53, v58
	v_mov_b32_e32 v30, v236
	v_mov_b32_e32 v31, v237
	v_mov_b32_e32 v32, v238
	v_mov_b32_e32 v33, v239
	v_mul_f32_e32 v4, v4, v30
	v_mul_f32_e32 v5, v5, v31
	v_mul_f32_e32 v6, v6, v32
	v_mul_f32_e32 v7, v7, v33
	v_cvt_pk_bf16_f32 v4, v4, v5
	v_cvt_pk_bf16_f32 v5, v6, v7
	v_mul_f32_e32 v30, v34, v30
	v_mul_f32_e32 v31, v35, v31
	v_mul_f32_e32 v32, v36, v32
	v_mul_f32_e32 v33, v37, v33
	v_cvt_pk_bf16_f32 v6, v30, v31
	v_cvt_pk_bf16_f32 v7, v32, v33
	global_store_dwordx2 v[20:21], v[4:5], off
	global_store_dwordx2 v[60:61], v[6:7], off offset:1024
	v_mul_f32_e32 v30, v55, v58
	v_mul_f32_e32 v31, v56, v58
	v_mul_f32_e32 v32, v57, v58
	v_mov_b32_e32 v4, v244
	v_mov_b32_e32 v5, v245
	v_mov_b32_e32 v6, v246
	v_mov_b32_e32 v7, v247
	v_mul_f32_e32 v0, v0, v4
	v_mul_f32_e32 v1, v1, v5
	v_mul_f32_e32 v2, v2, v6
	v_mul_f32_e32 v3, v3, v7
	v_cvt_pk_bf16_f32 v0, v0, v1
	v_cvt_pk_bf16_f32 v1, v2, v3
	v_mul_f32_e32 v4, v13, v4
	v_mul_f32_e32 v5, v30, v5
	v_mul_f32_e32 v6, v31, v6
	v_mul_f32_e32 v7, v32, v7
	v_cvt_pk_bf16_f32 v2, v4, v5
	v_cvt_pk_bf16_f32 v3, v6, v7
	global_store_dwordx2 v[20:21], v[0:1], off offset:512
	global_store_dwordx2 v[60:61], v[2:3], off offset:1536
	v_lshl_add_u64 v[20:21], v[20:21], 0, s[2:3]
	s_cbranch_scc0 .LBB0_404
	s_add_i32 s2, s96, s29
